# MoBA softmax VALU diet: unselected-query masking folded into the exp offset (-inf) instead of 16 per-tile P selects; redundant max canonicalisations removed
# speedup vs baseline: 1.0042x; 1.0037x over previous
.LBB0_890:
	s_nop 10
	v_max_f32_e32 v2, v84, v68
	v_max3_f32 v2, v2, v85, v69
	v_max3_f32 v2, v2, v86, v70
	v_max3_f32 v2, v2, v87, v71
	v_max3_f32 v2, v2, v88, v72
	v_max3_f32 v2, v2, v89, v73
	v_max3_f32 v2, v2, v90, v74
	v_max3_f32 v2, v2, v91, v75
	v_max3_f32 v2, v2, v92, v76
	v_max3_f32 v2, v2, v93, v77
	v_max3_f32 v2, v2, v94, v78
	v_max3_f32 v2, v2, v95, v79
	v_max3_f32 v2, v2, v96, v80
	v_max3_f32 v2, v2, v97, v81
	v_max3_f32 v2, v2, v98, v82
	v_max3_f32 v2, v2, v99, v83
	v_mov_b32_e32 v214, v2
	s_nop 1
	v_permlane32_swap_b32_e32 v2, v214
	v_max_f32_e32 v2, v2, v214
	s_or_b64 s[10:11], s[10:11], s[12:13]
	v_cndmask_b32_e64 v2, v210, v2, s[10:11]
	v_max_f32_e32 v2, v179, v2
	v_cmp_neq_f32_e32 vcc, v2, v179
	s_cbranch_vccz .LBB0_892
	v_sub_f32_e32 v179, v179, v2
	v_mul_f32_e32 v179, 0x3e0293ee, v179
	v_exp_f32_e32 v214, v179
	v_mov_b32_e32 v179, v2
	v_pk_mul_f32 v[66:67], v[66:67], v[214:215] op_sel_hi:[1,0]
	v_pk_mul_f32 v[64:65], v[64:65], v[214:215] op_sel_hi:[1,0]
	v_pk_mul_f32 v[62:63], v[62:63], v[214:215] op_sel_hi:[1,0]
	v_pk_mul_f32 v[60:61], v[60:61], v[214:215] op_sel_hi:[1,0]
	v_pk_mul_f32 v[58:59], v[58:59], v[214:215] op_sel_hi:[1,0]
	v_pk_mul_f32 v[56:57], v[56:57], v[214:215] op_sel_hi:[1,0]
	v_pk_mul_f32 v[54:55], v[54:55], v[214:215] op_sel_hi:[1,0]
	v_pk_mul_f32 v[52:53], v[52:53], v[214:215] op_sel_hi:[1,0]
	v_pk_mul_f32 v[50:51], v[50:51], v[214:215] op_sel_hi:[1,0]
	v_pk_mul_f32 v[48:49], v[48:49], v[214:215] op_sel_hi:[1,0]
	v_pk_mul_f32 v[46:47], v[46:47], v[214:215] op_sel_hi:[1,0]
	v_pk_mul_f32 v[44:45], v[44:45], v[214:215] op_sel_hi:[1,0]
	v_pk_mul_f32 v[42:43], v[42:43], v[214:215] op_sel_hi:[1,0]
	v_pk_mul_f32 v[40:41], v[40:41], v[214:215] op_sel_hi:[1,0]
	v_pk_mul_f32 v[38:39], v[38:39], v[214:215] op_sel_hi:[1,0]
	v_pk_mul_f32 v[36:37], v[36:37], v[214:215] op_sel_hi:[1,0]
	v_pk_mul_f32 v[34:35], v[34:35], v[214:215] op_sel_hi:[1,0]
	v_pk_mul_f32 v[32:33], v[32:33], v[214:215] op_sel_hi:[1,0]
	v_pk_mul_f32 v[30:31], v[30:31], v[214:215] op_sel_hi:[1,0]
	v_pk_mul_f32 v[28:29], v[28:29], v[214:215] op_sel_hi:[1,0]
	v_pk_mul_f32 v[26:27], v[26:27], v[214:215] op_sel_hi:[1,0]
	v_pk_mul_f32 v[24:25], v[24:25], v[214:215] op_sel_hi:[1,0]
	v_pk_mul_f32 v[22:23], v[22:23], v[214:215] op_sel_hi:[1,0]
	v_pk_mul_f32 v[20:21], v[20:21], v[214:215] op_sel_hi:[1,0]
	v_pk_mul_f32 v[18:19], v[18:19], v[214:215] op_sel_hi:[1,0]
	v_pk_mul_f32 v[16:17], v[16:17], v[214:215] op_sel_hi:[1,0]
	v_pk_mul_f32 v[14:15], v[14:15], v[214:215] op_sel_hi:[1,0]
	v_pk_mul_f32 v[12:13], v[12:13], v[214:215] op_sel_hi:[1,0]
	v_pk_mul_f32 v[10:11], v[10:11], v[214:215] op_sel_hi:[1,0]
	v_pk_mul_f32 v[8:9], v[8:9], v[214:215] op_sel_hi:[1,0]
	v_pk_mul_f32 v[6:7], v[6:7], v[214:215] op_sel_hi:[1,0]
	v_pk_mul_f32 v[4:5], v[4:5], v[214:215] op_sel_hi:[1,0]
	v_mul_f32_e32 v177, v177, v214
	s_branch .LBB0_893

.LBB0_893:
	v_mul_f32_e32 v216, 0xbe0293ee, v2
	v_cndmask_b32_e64 v216, v210, v216, s[10:11]
	v_fmamk_f32 v2, v84, 0x3e0293ee, v216
	v_exp_f32_e32 v217, v2
	v_fmamk_f32 v2, v68, 0x3e0293ee, v216
	v_exp_f32_e32 v218, v2
	v_fmamk_f32 v2, v85, 0x3e0293ee, v216
	v_fmamk_f32 v68, v69, 0x3e0293ee, v216
	v_exp_f32_e32 v2, v2
	v_exp_f32_e32 v214, v68
	v_add_f32_e32 v215, v218, v217
	v_pk_add_f32 v[68:69], v[214:215], v[2:3]
	s_nop 0
	v_pk_add_f32 v[68:69], v[68:69], v[68:69] op_sel_hi:[0,1]
	v_fmamk_f32 v68, v86, 0x3e0293ee, v216
	v_exp_f32_e32 v215, v68
	v_fmamk_f32 v68, v70, 0x3e0293ee, v216
	v_exp_f32_e32 v219, v68
	v_fmamk_f32 v68, v87, 0x3e0293ee, v216
	v_fmamk_f32 v70, v71, 0x3e0293ee, v216
	v_exp_f32_e32 v68, v68
	v_exp_f32_e32 v84, v70
	v_add_f32_e32 v85, v219, v215
	v_cvt_pk_bf16_f32 v2, v217, v2
	v_pk_add_f32 v[70:71], v[84:85], v[68:69]
	s_nop 0
	v_pk_add_f32 v[70:71], v[70:71], v[70:71] op_sel_hi:[0,1]
	v_fmamk_f32 v69, v88, 0x3e0293ee, v216
	v_fmamk_f32 v70, v72, 0x3e0293ee, v216
	v_exp_f32_e32 v69, v69
	v_exp_f32_e32 v85, v70
	v_fmamk_f32 v70, v89, 0x3e0293ee, v216
	v_fmamk_f32 v72, v73, 0x3e0293ee, v216
	v_exp_f32_e32 v70, v70
	v_exp_f32_e32 v86, v72
	v_add_f32_e32 v87, v85, v69
	v_pk_add_f32 v[72:73], v[86:87], v[70:71]
	s_nop 0
	v_pk_add_f32 v[72:73], v[72:73], v[72:73] op_sel_hi:[0,1]
	v_fmamk_f32 v71, v90, 0x3e0293ee, v216
	v_fmamk_f32 v72, v74, 0x3e0293ee, v216
	v_exp_f32_e32 v71, v71
	v_exp_f32_e32 v87, v72
	v_fmamk_f32 v72, v91, 0x3e0293ee, v216
	v_fmamk_f32 v74, v75, 0x3e0293ee, v216
	v_exp_f32_e32 v72, v72
	v_exp_f32_e32 v88, v74
	v_add_f32_e32 v89, v87, v71
	v_cvt_pk_bf16_f32 v70, v69, v70
	v_cvt_pk_bf16_f32 v71, v71, v72
	v_pk_add_f32 v[74:75], v[88:89], v[72:73]
	v_fmamk_f32 v73, v92, 0x3e0293ee, v216
	v_pk_add_f32 v[74:75], v[74:75], v[74:75] op_sel_hi:[0,1]
	v_fmamk_f32 v74, v76, 0x3e0293ee, v216
	v_exp_f32_e32 v73, v73
	v_exp_f32_e32 v89, v74
	v_fmamk_f32 v74, v93, 0x3e0293ee, v216
	v_fmamk_f32 v76, v77, 0x3e0293ee, v216
	v_exp_f32_e32 v74, v74
	v_exp_f32_e32 v90, v76
	v_add_f32_e32 v91, v89, v73
	v_pk_add_f32 v[76:77], v[90:91], v[74:75]
	v_fmamk_f32 v75, v94, 0x3e0293ee, v216
	v_pk_add_f32 v[76:77], v[76:77], v[76:77] op_sel_hi:[0,1]
	v_fmamk_f32 v76, v78, 0x3e0293ee, v216
	v_exp_f32_e32 v75, v75
	v_exp_f32_e32 v91, v76
	v_fmamk_f32 v76, v95, 0x3e0293ee, v216
	v_fmamk_f32 v78, v79, 0x3e0293ee, v216
	v_exp_f32_e32 v76, v76
	v_exp_f32_e32 v92, v78
	v_add_f32_e32 v93, v91, v75
	v_pk_add_f32 v[78:79], v[92:93], v[76:77]
	s_nop 0
	v_pk_add_f32 v[78:79], v[78:79], v[78:79] op_sel_hi:[0,1]
	v_fmamk_f32 v77, v96, 0x3e0293ee, v216
	v_fmamk_f32 v78, v80, 0x3e0293ee, v216
	v_exp_f32_e32 v77, v77
	v_exp_f32_e32 v93, v78
	v_fmamk_f32 v78, v97, 0x3e0293ee, v216
	v_fmamk_f32 v80, v81, 0x3e0293ee, v216
	v_exp_f32_e32 v78, v78
	v_exp_f32_e32 v94, v80
	v_add_f32_e32 v95, v93, v77
	v_pk_add_f32 v[80:81], v[94:95], v[78:79]
	s_nop 0
	v_pk_add_f32 v[80:81], v[80:81], v[80:81] op_sel_hi:[0,1]
	v_fmamk_f32 v79, v98, 0x3e0293ee, v216
	v_fmamk_f32 v80, v82, 0x3e0293ee, v216
	v_exp_f32_e32 v79, v79
	v_exp_f32_e32 v95, v80
	v_fmamk_f32 v80, v99, 0x3e0293ee, v216
	v_fmac_f32_e32 v216, 0x3e0293ee, v83
	v_exp_f32_e32 v80, v80
	v_exp_f32_e32 v96, v216
	v_add_f32_e32 v97, v95, v79
	v_pk_add_f32 v[82:83], v[96:97], v[80:81]
	s_nop 0
	v_pk_add_f32 v[82:83], v[82:83], v[82:83] op_sel:[0,1] op_sel_hi:[1,0]
	s_nop 0
	v_mov_b32_e32 v81, v82
	s_nop 1
	v_permlane32_swap_b32_e32 v82, v81
	v_add_f32_e32 v81, v82, v81
	v_cndmask_b32_e64 v230, 0, v81, s[10:11]
	v_cvt_pk_bf16_f32 v69, v215, v68
	v_mov_b32_e32 v68, v2
	v_cvt_pk_bf16_f32 v72, v73, v74
	v_cvt_pk_bf16_f32 v2, v218, v214
	v_cvt_pk_bf16_f32 v73, v75, v76
	v_mov_b32_e32 v76, v2
	v_cvt_pk_bf16_f32 v2, v89, v90
	v_cvt_pk_bf16_f32 v75, v79, v80
	v_mov_b32_e32 v80, v2
	v_add3_u32 v2, s24, v163, v206
	v_add_u32_e32 v231, 0x4000, v2
	v_add_u32_e32 v232, 0x5000, v2
	v_add_u32_e32 v233, 0x6000, v2
	v_add_u32_e32 v2, 0x7000, v2
	v_cvt_pk_bf16_f32 v74, v77, v78
	v_cvt_pk_bf16_f32 v77, v219, v84
	v_cvt_pk_bf16_f32 v78, v85, v86
	v_cvt_pk_bf16_f32 v79, v87, v88
	v_cvt_pk_bf16_f32 v81, v91, v92
	v_cvt_pk_bf16_f32 v82, v93, v94
	v_cvt_pk_bf16_f32 v83, v95, v96
	ds_read2_b64 v[84:87], v231 offset0:128 offset1:130
	ds_read2_b64 v[88:91], v231 offset0:132 offset1:134
	ds_read2_b64 v[92:95], v232 offset0:160 offset1:162
	ds_read2_b64 v[96:99], v233 offset0:192 offset1:194
	ds_read2_b64 v[214:217], v2 offset0:224 offset1:226
	ds_read2_b64 v[218:221], v232 offset0:164 offset1:166
	ds_read2_b64 v[222:225], v233 offset0:196 offset1:198
	ds_read2_b64 v[226:229], v2 offset0:228 offset1:230
	s_waitcnt lgkmcnt(7)
	v_mfma_f32_32x32x16_bf16 v[52:67], v[84:87], v[68:71], v[52:67]
	s_waitcnt lgkmcnt(5)
	v_mfma_f32_32x32x16_bf16 v[36:51], v[92:95], v[68:71], v[36:51]
	s_waitcnt lgkmcnt(4)
	v_mfma_f32_32x32x16_bf16 v[20:35], v[96:99], v[68:71], v[20:35]
	s_waitcnt lgkmcnt(3)
	v_mfma_f32_32x32x16_bf16 v[4:19], v[214:217], v[68:71], v[4:19]
	ds_read2_b64 v[68:71], v231 offset0:136 offset1:138
	ds_read2_b64 v[84:87], v232 offset0:168 offset1:170
	ds_read2_b64 v[92:95], v233 offset0:200 offset1:202
	ds_read2_b64 v[96:99], v2 offset0:232 offset1:234
	v_mfma_f32_32x32x16_bf16 v[52:67], v[88:91], v[72:75], v[52:67]
	s_waitcnt lgkmcnt(6)
	v_mfma_f32_32x32x16_bf16 v[36:51], v[218:221], v[72:75], v[36:51]
	s_waitcnt lgkmcnt(5)
	v_mfma_f32_32x32x16_bf16 v[20:35], v[222:225], v[72:75], v[20:35]
	s_waitcnt lgkmcnt(4)
	v_mfma_f32_32x32x16_bf16 v[4:19], v[226:229], v[72:75], v[4:19]
	ds_read2_b64 v[72:75], v231 offset0:140 offset1:142
	ds_read2_b64 v[88:91], v232 offset0:172 offset1:174
	ds_read2_b64 v[214:217], v233 offset0:204 offset1:206
	ds_read2_b64 v[218:221], v2 offset0:236 offset1:238
	s_waitcnt lgkmcnt(7)
	v_mfma_f32_32x32x16_bf16 v[52:67], v[68:71], v[76:79], v[52:67]
	s_waitcnt lgkmcnt(6)
	v_mfma_f32_32x32x16_bf16 v[36:51], v[84:87], v[76:79], v[36:51]
	s_waitcnt lgkmcnt(5)
	v_mfma_f32_32x32x16_bf16 v[20:35], v[92:95], v[76:79], v[20:35]
	s_waitcnt lgkmcnt(4)
	v_mfma_f32_32x32x16_bf16 v[4:19], v[96:99], v[76:79], v[4:19]
	s_waitcnt lgkmcnt(3)
	v_mfma_f32_32x32x16_bf16 v[52:67], v[72:75], v[80:83], v[52:67]
	v_add_f32_e32 v177, v177, v230
	s_waitcnt lgkmcnt(2)
	v_mfma_f32_32x32x16_bf16 v[36:51], v[88:91], v[80:83], v[36:51]
	s_waitcnt lgkmcnt(1)
	v_mfma_f32_32x32x16_bf16 v[20:35], v[214:217], v[80:83], v[20:35]
	s_waitcnt lgkmcnt(0)
	v_mfma_f32_32x32x16_bf16 v[4:19], v[218:221], v[80:83], v[4:19]

.LBB0_901:
	s_nop 10
	v_max_f32_e32 v2, v84, v68
	v_max3_f32 v2, v2, v85, v69
	v_max3_f32 v2, v2, v86, v70
	v_max3_f32 v2, v2, v87, v71
	v_max3_f32 v2, v2, v88, v72
	v_max3_f32 v2, v2, v89, v73
	v_max3_f32 v2, v2, v90, v74
	v_max3_f32 v2, v2, v91, v75
	v_max3_f32 v2, v2, v92, v76
	v_max3_f32 v2, v2, v93, v77
	v_max3_f32 v2, v2, v94, v78
	v_max3_f32 v2, v2, v95, v79
	v_max3_f32 v2, v2, v96, v80
	v_max3_f32 v2, v2, v97, v81
	v_max3_f32 v2, v2, v98, v82
	v_max3_f32 v2, v2, v99, v83
	v_mov_b32_e32 v100, v2
	s_nop 1
	v_permlane32_swap_b32_e32 v2, v100
	v_max_f32_e32 v2, v2, v100
	s_or_b64 s[10:11], s[20:21], s[10:11]
	v_cndmask_b32_e64 v2, v210, v2, s[10:11]
	v_max_f32_e32 v2, v179, v2
	v_cmp_neq_f32_e32 vcc, v2, v179
	s_cbranch_vccz .LBB0_903
	v_sub_f32_e32 v100, v179, v2
	v_mul_f32_e32 v100, 0x3e0293ee, v100
	v_exp_f32_e32 v100, v100
	s_nop 0
	v_pk_mul_f32 v[66:67], v[66:67], v[100:101] op_sel_hi:[1,0]
	v_pk_mul_f32 v[64:65], v[64:65], v[100:101] op_sel_hi:[1,0]
	v_pk_mul_f32 v[62:63], v[62:63], v[100:101] op_sel_hi:[1,0]
	v_pk_mul_f32 v[60:61], v[60:61], v[100:101] op_sel_hi:[1,0]
	v_pk_mul_f32 v[58:59], v[58:59], v[100:101] op_sel_hi:[1,0]
	v_pk_mul_f32 v[56:57], v[56:57], v[100:101] op_sel_hi:[1,0]
	v_pk_mul_f32 v[54:55], v[54:55], v[100:101] op_sel_hi:[1,0]
	v_pk_mul_f32 v[52:53], v[52:53], v[100:101] op_sel_hi:[1,0]
	v_pk_mul_f32 v[50:51], v[50:51], v[100:101] op_sel_hi:[1,0]
	v_pk_mul_f32 v[48:49], v[48:49], v[100:101] op_sel_hi:[1,0]
	v_pk_mul_f32 v[46:47], v[46:47], v[100:101] op_sel_hi:[1,0]
	v_pk_mul_f32 v[44:45], v[44:45], v[100:101] op_sel_hi:[1,0]
	v_pk_mul_f32 v[42:43], v[42:43], v[100:101] op_sel_hi:[1,0]
	v_pk_mul_f32 v[40:41], v[40:41], v[100:101] op_sel_hi:[1,0]
	v_pk_mul_f32 v[38:39], v[38:39], v[100:101] op_sel_hi:[1,0]
	v_pk_mul_f32 v[36:37], v[36:37], v[100:101] op_sel_hi:[1,0]
	v_pk_mul_f32 v[34:35], v[34:35], v[100:101] op_sel_hi:[1,0]
	v_pk_mul_f32 v[32:33], v[32:33], v[100:101] op_sel_hi:[1,0]
	v_pk_mul_f32 v[30:31], v[30:31], v[100:101] op_sel_hi:[1,0]
	v_pk_mul_f32 v[28:29], v[28:29], v[100:101] op_sel_hi:[1,0]
	v_pk_mul_f32 v[26:27], v[26:27], v[100:101] op_sel_hi:[1,0]
	v_pk_mul_f32 v[24:25], v[24:25], v[100:101] op_sel_hi:[1,0]
	v_pk_mul_f32 v[22:23], v[22:23], v[100:101] op_sel_hi:[1,0]
	v_pk_mul_f32 v[20:21], v[20:21], v[100:101] op_sel_hi:[1,0]
	v_pk_mul_f32 v[18:19], v[18:19], v[100:101] op_sel_hi:[1,0]
	v_pk_mul_f32 v[16:17], v[16:17], v[100:101] op_sel_hi:[1,0]
	v_pk_mul_f32 v[14:15], v[14:15], v[100:101] op_sel_hi:[1,0]
	v_pk_mul_f32 v[12:13], v[12:13], v[100:101] op_sel_hi:[1,0]
	v_pk_mul_f32 v[10:11], v[10:11], v[100:101] op_sel_hi:[1,0]
	v_pk_mul_f32 v[8:9], v[8:9], v[100:101] op_sel_hi:[1,0]
	v_pk_mul_f32 v[6:7], v[6:7], v[100:101] op_sel_hi:[1,0]
	v_pk_mul_f32 v[4:5], v[4:5], v[100:101] op_sel_hi:[1,0]
	v_mul_f32_e32 v177, v177, v100
	s_branch .LBB0_904

.LBB0_904:
	v_mul_f32_e32 v102, 0xbe0293ee, v2
	v_cndmask_b32_e64 v102, v210, v102, s[10:11]
	v_fmamk_f32 v2, v84, 0x3e0293ee, v102
	v_exp_f32_e32 v103, v2
	v_fmamk_f32 v2, v68, 0x3e0293ee, v102
	v_exp_f32_e32 v104, v2
	v_fmamk_f32 v2, v85, 0x3e0293ee, v102
	v_fmamk_f32 v68, v69, 0x3e0293ee, v102
	v_exp_f32_e32 v2, v2
	v_exp_f32_e32 v100, v68
	v_add_f32_e32 v101, v104, v103
	v_pk_add_f32 v[68:69], v[100:101], v[2:3]
	s_nop 0
	v_pk_add_f32 v[68:69], v[68:69], v[68:69] op_sel_hi:[0,1]
	v_fmamk_f32 v68, v86, 0x3e0293ee, v102
	v_exp_f32_e32 v101, v68
	v_fmamk_f32 v68, v70, 0x3e0293ee, v102
	v_exp_f32_e32 v105, v68
	v_fmamk_f32 v68, v87, 0x3e0293ee, v102
	v_fmamk_f32 v70, v71, 0x3e0293ee, v102
	v_exp_f32_e32 v68, v68
	v_exp_f32_e32 v84, v70
	v_add_f32_e32 v85, v105, v101
	v_cvt_pk_bf16_f32 v2, v103, v2
	v_pk_add_f32 v[70:71], v[84:85], v[68:69]
	s_nop 0
	v_pk_add_f32 v[70:71], v[70:71], v[70:71] op_sel_hi:[0,1]
	v_fmamk_f32 v69, v88, 0x3e0293ee, v102
	v_fmamk_f32 v70, v72, 0x3e0293ee, v102
	v_exp_f32_e32 v69, v69
	v_exp_f32_e32 v85, v70
	v_fmamk_f32 v70, v89, 0x3e0293ee, v102
	v_fmamk_f32 v72, v73, 0x3e0293ee, v102
	v_exp_f32_e32 v70, v70
	v_exp_f32_e32 v86, v72
	v_add_f32_e32 v87, v85, v69
	v_pk_add_f32 v[72:73], v[86:87], v[70:71]
	s_nop 0
	v_pk_add_f32 v[72:73], v[72:73], v[72:73] op_sel_hi:[0,1]
	v_fmamk_f32 v71, v90, 0x3e0293ee, v102
	v_fmamk_f32 v72, v74, 0x3e0293ee, v102
	v_exp_f32_e32 v71, v71
	v_exp_f32_e32 v87, v72
	v_fmamk_f32 v72, v91, 0x3e0293ee, v102
	v_fmamk_f32 v74, v75, 0x3e0293ee, v102
	v_exp_f32_e32 v72, v72
	v_exp_f32_e32 v88, v74
	v_add_f32_e32 v89, v87, v71
	v_cvt_pk_bf16_f32 v70, v69, v70
	v_cvt_pk_bf16_f32 v71, v71, v72
	v_pk_add_f32 v[74:75], v[88:89], v[72:73]
	v_fmamk_f32 v73, v92, 0x3e0293ee, v102
	v_pk_add_f32 v[74:75], v[74:75], v[74:75] op_sel_hi:[0,1]
	v_fmamk_f32 v74, v76, 0x3e0293ee, v102
	v_exp_f32_e32 v73, v73
	v_exp_f32_e32 v89, v74
	v_fmamk_f32 v74, v93, 0x3e0293ee, v102
	v_fmamk_f32 v76, v77, 0x3e0293ee, v102
	v_exp_f32_e32 v74, v74
	v_exp_f32_e32 v90, v76
	v_add_f32_e32 v91, v89, v73
	v_pk_add_f32 v[76:77], v[90:91], v[74:75]
	v_fmamk_f32 v75, v94, 0x3e0293ee, v102
	v_pk_add_f32 v[76:77], v[76:77], v[76:77] op_sel_hi:[0,1]
	v_fmamk_f32 v76, v78, 0x3e0293ee, v102
	v_exp_f32_e32 v75, v75
	v_exp_f32_e32 v91, v76
	v_fmamk_f32 v76, v95, 0x3e0293ee, v102
	v_fmamk_f32 v78, v79, 0x3e0293ee, v102
	v_exp_f32_e32 v76, v76
	v_exp_f32_e32 v92, v78
	v_add_f32_e32 v93, v91, v75
	v_pk_add_f32 v[78:79], v[92:93], v[76:77]
	s_nop 0
	v_pk_add_f32 v[78:79], v[78:79], v[78:79] op_sel_hi:[0,1]
	v_fmamk_f32 v77, v96, 0x3e0293ee, v102
	v_fmamk_f32 v78, v80, 0x3e0293ee, v102
	v_exp_f32_e32 v77, v77
	v_exp_f32_e32 v93, v78
	v_fmamk_f32 v78, v97, 0x3e0293ee, v102
	v_fmamk_f32 v80, v81, 0x3e0293ee, v102
	v_exp_f32_e32 v78, v78
	v_exp_f32_e32 v94, v80
	v_add_f32_e32 v95, v93, v77
	v_pk_add_f32 v[80:81], v[94:95], v[78:79]
	s_nop 0
	v_pk_add_f32 v[80:81], v[80:81], v[80:81] op_sel_hi:[0,1]
	v_fmamk_f32 v79, v98, 0x3e0293ee, v102
	v_fmamk_f32 v80, v82, 0x3e0293ee, v102
	v_exp_f32_e32 v79, v79
	v_exp_f32_e32 v95, v80
	v_fmamk_f32 v80, v99, 0x3e0293ee, v102
	v_fmac_f32_e32 v102, 0x3e0293ee, v83
	v_exp_f32_e32 v80, v80
	v_exp_f32_e32 v96, v102
	v_add_f32_e32 v97, v95, v79
	v_pk_add_f32 v[82:83], v[96:97], v[80:81]
	s_nop 0
	v_pk_add_f32 v[82:83], v[82:83], v[82:83] op_sel:[0,1] op_sel_hi:[1,0]
	s_nop 0
	v_mov_b32_e32 v81, v82
	s_nop 1
	v_permlane32_swap_b32_e32 v82, v81
	v_add_f32_e32 v81, v82, v81
	v_cndmask_b32_e64 v116, 0, v81, s[10:11]
	v_cvt_pk_bf16_f32 v69, v101, v68
	v_mov_b32_e32 v68, v2
	v_cvt_pk_bf16_f32 v72, v73, v74
	v_cvt_pk_bf16_f32 v2, v104, v100
	v_cvt_pk_bf16_f32 v73, v75, v76
	v_mov_b32_e32 v76, v2
	v_cvt_pk_bf16_f32 v2, v89, v90
	v_cvt_pk_bf16_f32 v75, v79, v80
	v_mov_b32_e32 v80, v2
	v_add3_u32 v2, s14, v163, v206
	v_add_u32_e32 v117, 0x4000, v2
	v_add_u32_e32 v118, 0x5000, v2
	v_add_u32_e32 v119, 0x6000, v2
	v_add_u32_e32 v2, 0x7000, v2
	v_cvt_pk_bf16_f32 v74, v77, v78
	v_cvt_pk_bf16_f32 v77, v105, v84
	v_cvt_pk_bf16_f32 v78, v85, v86
	v_cvt_pk_bf16_f32 v79, v87, v88
	v_cvt_pk_bf16_f32 v81, v91, v92
	v_cvt_pk_bf16_f32 v82, v93, v94
	v_cvt_pk_bf16_f32 v83, v95, v96
	ds_read2_b64 v[84:87], v117 offset0:128 offset1:130
	ds_read2_b64 v[88:91], v117 offset0:132 offset1:134
	ds_read2_b64 v[92:95], v118 offset0:160 offset1:162
	ds_read2_b64 v[96:99], v119 offset0:192 offset1:194
	ds_read2_b64 v[100:103], v2 offset0:224 offset1:226
	ds_read2_b64 v[104:107], v118 offset0:164 offset1:166
	ds_read2_b64 v[108:111], v119 offset0:196 offset1:198
	ds_read2_b64 v[112:115], v2 offset0:228 offset1:230
	s_waitcnt lgkmcnt(7)
	v_mfma_f32_32x32x16_bf16 v[52:67], v[84:87], v[68:71], v[52:67]
	s_waitcnt lgkmcnt(5)
	v_mfma_f32_32x32x16_bf16 v[36:51], v[92:95], v[68:71], v[36:51]
	s_waitcnt lgkmcnt(4)
	v_mfma_f32_32x32x16_bf16 v[20:35], v[96:99], v[68:71], v[20:35]
	s_waitcnt lgkmcnt(3)
	v_mfma_f32_32x32x16_bf16 v[4:19], v[100:103], v[68:71], v[4:19]
	ds_read2_b64 v[68:71], v117 offset0:136 offset1:138
	ds_read2_b64 v[84:87], v118 offset0:168 offset1:170
	ds_read2_b64 v[92:95], v119 offset0:200 offset1:202
	ds_read2_b64 v[96:99], v2 offset0:232 offset1:234
	v_mfma_f32_32x32x16_bf16 v[52:67], v[88:91], v[72:75], v[52:67]
	s_waitcnt lgkmcnt(6)
	v_mfma_f32_32x32x16_bf16 v[36:51], v[104:107], v[72:75], v[36:51]
	s_waitcnt lgkmcnt(5)
	v_mfma_f32_32x32x16_bf16 v[20:35], v[108:111], v[72:75], v[20:35]
	s_waitcnt lgkmcnt(4)
	v_mfma_f32_32x32x16_bf16 v[4:19], v[112:115], v[72:75], v[4:19]
	ds_read2_b64 v[72:75], v117 offset0:140 offset1:142
	ds_read2_b64 v[88:91], v118 offset0:172 offset1:174
	ds_read2_b64 v[100:103], v119 offset0:204 offset1:206
	ds_read2_b64 v[104:107], v2 offset0:236 offset1:238
	s_waitcnt lgkmcnt(7)
	v_mfma_f32_32x32x16_bf16 v[52:67], v[68:71], v[76:79], v[52:67]
	s_waitcnt lgkmcnt(6)
	v_mfma_f32_32x32x16_bf16 v[36:51], v[84:87], v[76:79], v[36:51]
	s_waitcnt lgkmcnt(5)
	v_mfma_f32_32x32x16_bf16 v[20:35], v[92:95], v[76:79], v[20:35]
	s_waitcnt lgkmcnt(4)
	v_mfma_f32_32x32x16_bf16 v[4:19], v[96:99], v[76:79], v[4:19]
	s_waitcnt lgkmcnt(3)
	v_mfma_f32_32x32x16_bf16 v[52:67], v[72:75], v[80:83], v[52:67]
	v_add_f32_e32 v177, v177, v116
	s_waitcnt lgkmcnt(2)
	v_mfma_f32_32x32x16_bf16 v[36:51], v[88:91], v[80:83], v[36:51]
	s_waitcnt lgkmcnt(1)
	v_mfma_f32_32x32x16_bf16 v[20:35], v[100:103], v[80:83], v[20:35]
	s_waitcnt lgkmcnt(0)
	v_mfma_f32_32x32x16_bf16 v[4:19], v[104:107], v[80:83], v[4:19]

.LBB0_921:
	s_nop 10
	v_max_f32_e32 v2, v98, v82
	v_max3_f32 v2, v2, v99, v83
	v_max3_f32 v2, v2, v100, v84
	v_max3_f32 v2, v2, v101, v85
	v_max3_f32 v2, v2, v102, v86
	v_max3_f32 v2, v2, v103, v87
	v_max3_f32 v2, v2, v104, v88
	v_max3_f32 v2, v2, v105, v89
	v_max3_f32 v2, v2, v106, v90
	v_max3_f32 v2, v2, v107, v91
	v_max3_f32 v2, v2, v108, v92
	v_max3_f32 v2, v2, v109, v93
	v_max3_f32 v2, v2, v110, v94
	v_max3_f32 v2, v2, v111, v95
	v_max3_f32 v2, v2, v112, v96
	v_max3_f32 v2, v2, v113, v97
	v_mov_b32_e32 v16, v2
	s_nop 1
	v_permlane32_swap_b32_e32 v2, v16
	v_max_f32_e32 v2, v2, v16
	s_or_b64 s[10:11], s[10:11], s[12:13]
	v_cndmask_b32_e64 v2, v210, v2, s[10:11]
	v_max_f32_e32 v2, v174, v2
	v_cmp_neq_f32_e32 vcc, v2, v174
	s_cbranch_vccz .LBB0_923
	v_sub_f32_e32 v16, v174, v2
	v_mul_f32_e32 v16, 0x3e0293ee, v16
	v_exp_f32_e32 v16, v16
	v_mov_b32_e32 v174, v2
	v_pk_mul_f32 v[80:81], v[80:81], v[16:17] op_sel_hi:[1,0]
	v_pk_mul_f32 v[78:79], v[78:79], v[16:17] op_sel_hi:[1,0]
	v_pk_mul_f32 v[76:77], v[76:77], v[16:17] op_sel_hi:[1,0]
	v_pk_mul_f32 v[74:75], v[74:75], v[16:17] op_sel_hi:[1,0]
	v_pk_mul_f32 v[72:73], v[72:73], v[16:17] op_sel_hi:[1,0]
	v_pk_mul_f32 v[70:71], v[70:71], v[16:17] op_sel_hi:[1,0]
	v_pk_mul_f32 v[68:69], v[68:69], v[16:17] op_sel_hi:[1,0]
	v_pk_mul_f32 v[66:67], v[66:67], v[16:17] op_sel_hi:[1,0]
	v_pk_mul_f32 v[64:65], v[64:65], v[16:17] op_sel_hi:[1,0]
	v_pk_mul_f32 v[62:63], v[62:63], v[16:17] op_sel_hi:[1,0]
	v_pk_mul_f32 v[60:61], v[60:61], v[16:17] op_sel_hi:[1,0]
	v_pk_mul_f32 v[58:59], v[58:59], v[16:17] op_sel_hi:[1,0]
	v_pk_mul_f32 v[56:57], v[56:57], v[16:17] op_sel_hi:[1,0]
	v_pk_mul_f32 v[54:55], v[54:55], v[16:17] op_sel_hi:[1,0]
	v_pk_mul_f32 v[52:53], v[52:53], v[16:17] op_sel_hi:[1,0]
	v_pk_mul_f32 v[50:51], v[50:51], v[16:17] op_sel_hi:[1,0]
	v_pk_mul_f32 v[48:49], v[48:49], v[16:17] op_sel_hi:[1,0]
	v_pk_mul_f32 v[46:47], v[46:47], v[16:17] op_sel_hi:[1,0]
	v_pk_mul_f32 v[44:45], v[44:45], v[16:17] op_sel_hi:[1,0]
	v_pk_mul_f32 v[42:43], v[42:43], v[16:17] op_sel_hi:[1,0]
	v_pk_mul_f32 v[40:41], v[40:41], v[16:17] op_sel_hi:[1,0]
	v_pk_mul_f32 v[38:39], v[38:39], v[16:17] op_sel_hi:[1,0]
	v_pk_mul_f32 v[36:37], v[36:37], v[16:17] op_sel_hi:[1,0]
	v_pk_mul_f32 v[34:35], v[34:35], v[16:17] op_sel_hi:[1,0]
	v_pk_mul_f32 v[32:33], v[32:33], v[16:17] op_sel_hi:[1,0]
	v_pk_mul_f32 v[30:31], v[30:31], v[16:17] op_sel_hi:[1,0]
	v_pk_mul_f32 v[28:29], v[28:29], v[16:17] op_sel_hi:[1,0]
	v_pk_mul_f32 v[26:27], v[26:27], v[16:17] op_sel_hi:[1,0]
	v_pk_mul_f32 v[24:25], v[24:25], v[16:17] op_sel_hi:[1,0]
	v_pk_mul_f32 v[22:23], v[22:23], v[16:17] op_sel_hi:[1,0]
	v_pk_mul_f32 v[20:21], v[20:21], v[16:17] op_sel_hi:[1,0]
	v_pk_mul_f32 v[18:19], v[18:19], v[16:17] op_sel_hi:[1,0]
	v_mul_f32_e32 v172, v172, v16
	s_branch .LBB0_924

.LBB0_924:
	v_mul_f32_e32 v175, 0xbe0293ee, v2
	v_cndmask_b32_e64 v175, v210, v175, s[10:11]
	v_fmamk_f32 v2, v98, 0x3e0293ee, v175
	v_exp_f32_e32 v176, v2
	v_fmamk_f32 v2, v82, 0x3e0293ee, v175
	v_exp_f32_e32 v177, v2
	v_fmamk_f32 v2, v99, 0x3e0293ee, v175
	v_fmamk_f32 v16, v83, 0x3e0293ee, v175
	v_exp_f32_e32 v2, v2
	v_exp_f32_e32 v16, v16
	v_add_f32_e32 v17, v177, v176
	v_pk_add_f32 v[82:83], v[16:17], v[2:3]
	s_nop 0
	v_pk_add_f32 v[82:83], v[82:83], v[82:83] op_sel_hi:[0,1]
	v_fmamk_f32 v17, v100, 0x3e0293ee, v175
	v_fmamk_f32 v82, v84, 0x3e0293ee, v175
	v_exp_f32_e32 v17, v17
	v_exp_f32_e32 v178, v82
	v_fmamk_f32 v82, v101, 0x3e0293ee, v175
	v_fmamk_f32 v84, v85, 0x3e0293ee, v175
	v_exp_f32_e32 v82, v82
	v_exp_f32_e32 v98, v84
	v_add_f32_e32 v99, v178, v17
	v_cvt_pk_bf16_f32 v2, v176, v2
	v_cvt_pk_bf16_f32 v17, v17, v82
	v_pk_add_f32 v[84:85], v[98:99], v[82:83]
	v_fmamk_f32 v83, v102, 0x3e0293ee, v175
	v_pk_add_f32 v[84:85], v[84:85], v[84:85] op_sel_hi:[0,1]
	v_fmamk_f32 v84, v86, 0x3e0293ee, v175
	v_exp_f32_e32 v83, v83
	v_exp_f32_e32 v99, v84
	v_fmamk_f32 v84, v103, 0x3e0293ee, v175
	v_fmamk_f32 v86, v87, 0x3e0293ee, v175
	v_exp_f32_e32 v84, v84
	v_exp_f32_e32 v100, v86
	v_add_f32_e32 v101, v99, v83
	v_mov_b32_e32 v82, v2
	v_pk_add_f32 v[86:87], v[100:101], v[84:85]
	s_nop 0
	v_pk_add_f32 v[86:87], v[86:87], v[86:87] op_sel_hi:[0,1]
	v_fmamk_f32 v85, v104, 0x3e0293ee, v175
	v_fmamk_f32 v86, v88, 0x3e0293ee, v175
	v_exp_f32_e32 v85, v85
	v_exp_f32_e32 v101, v86
	v_fmamk_f32 v86, v105, 0x3e0293ee, v175
	v_fmamk_f32 v88, v89, 0x3e0293ee, v175
	v_exp_f32_e32 v86, v86
	v_exp_f32_e32 v102, v88
	v_add_f32_e32 v103, v101, v85
	v_cvt_pk_bf16_f32 v84, v83, v84
	v_cvt_pk_bf16_f32 v85, v85, v86
	v_pk_add_f32 v[88:89], v[102:103], v[86:87]
	v_fmamk_f32 v87, v106, 0x3e0293ee, v175
	v_pk_add_f32 v[88:89], v[88:89], v[88:89] op_sel_hi:[0,1]
	v_fmamk_f32 v88, v90, 0x3e0293ee, v175
	v_exp_f32_e32 v87, v87
	v_exp_f32_e32 v103, v88
	v_fmamk_f32 v88, v107, 0x3e0293ee, v175
	v_fmamk_f32 v90, v91, 0x3e0293ee, v175
	v_exp_f32_e32 v88, v88
	v_exp_f32_e32 v104, v90
	v_add_f32_e32 v105, v103, v87
	v_mov_b32_e32 v83, v17
	v_cvt_pk_bf16_f32 v86, v87, v88
	v_pk_add_f32 v[90:91], v[104:105], v[88:89]
	v_fmamk_f32 v89, v108, 0x3e0293ee, v175
	v_pk_add_f32 v[90:91], v[90:91], v[90:91] op_sel_hi:[0,1]
	v_fmamk_f32 v90, v92, 0x3e0293ee, v175
	v_exp_f32_e32 v89, v89
	v_exp_f32_e32 v105, v90
	v_fmamk_f32 v90, v109, 0x3e0293ee, v175
	v_fmamk_f32 v92, v93, 0x3e0293ee, v175
	v_exp_f32_e32 v90, v90
	v_exp_f32_e32 v106, v92
	v_add_f32_e32 v107, v105, v89
	v_cvt_pk_bf16_f32 v87, v89, v90
	v_pk_add_f32 v[92:93], v[106:107], v[90:91]
	v_fmamk_f32 v91, v110, 0x3e0293ee, v175
	v_pk_add_f32 v[92:93], v[92:93], v[92:93] op_sel_hi:[0,1]
	v_fmamk_f32 v92, v94, 0x3e0293ee, v175
	v_exp_f32_e32 v91, v91
	v_exp_f32_e32 v107, v92
	v_fmamk_f32 v92, v111, 0x3e0293ee, v175
	v_fmamk_f32 v94, v95, 0x3e0293ee, v175
	v_exp_f32_e32 v92, v92
	v_exp_f32_e32 v108, v94
	v_add_f32_e32 v109, v107, v91
	v_cvt_pk_bf16_f32 v90, v177, v16
	v_pk_add_f32 v[94:95], v[108:109], v[92:93]
	v_fmamk_f32 v93, v112, 0x3e0293ee, v175
	v_pk_add_f32 v[94:95], v[94:95], v[94:95] op_sel_hi:[0,1]
	v_fmamk_f32 v94, v96, 0x3e0293ee, v175
	v_exp_f32_e32 v93, v93
	v_exp_f32_e32 v109, v94
	v_fmamk_f32 v94, v113, 0x3e0293ee, v175
	v_fmac_f32_e32 v175, 0x3e0293ee, v97
	v_exp_f32_e32 v94, v94
	v_exp_f32_e32 v110, v175
	v_add_f32_e32 v111, v109, v93
	v_cvt_pk_bf16_f32 v16, v178, v98
	v_cvt_pk_bf16_f32 v17, v99, v100
	v_pk_add_f32 v[96:97], v[110:111], v[94:95]
	v_pk_add_f32 v[96:97], v[96:97], v[96:97] op_sel:[0,1] op_sel_hi:[1,0]
	v_cvt_pk_bf16_f32 v2, v103, v104
	v_mov_b32_e32 v95, v96
	s_nop 1
	v_permlane32_swap_b32_e32 v96, v95
	v_add_f32_e32 v95, v96, v95
	v_cvt_pk_bf16_f32 v88, v91, v92
	v_cvt_pk_bf16_f32 v89, v93, v94
	v_mov_b32_e32 v91, v16
	v_mov_b32_e32 v92, v17
	v_cvt_pk_bf16_f32 v16, v105, v106
	v_cvt_pk_bf16_f32 v96, v107, v108
	v_mov_b32_e32 v94, v2
	v_add3_u32 v2, s20, v163, v206
	v_cndmask_b32_e64 v175, 0, v95, s[10:11]
	v_mov_b32_e32 v95, v16
	v_add_u32_e32 v16, 0x4000, v2
	v_add_u32_e32 v17, 0x5000, v2
	v_add_u32_e32 v211, 0x6000, v2
	v_add_u32_e32 v2, 0x7000, v2
	v_cvt_pk_bf16_f32 v93, v101, v102
	v_cvt_pk_bf16_f32 v97, v109, v110
	ds_read2_b64 v[98:101], v16 offset0:128 offset1:130
	ds_read2_b64 v[102:105], v16 offset0:132 offset1:134
	ds_read2_b64 v[106:109], v17 offset0:160 offset1:162
	ds_read2_b64 v[110:113], v211 offset0:192 offset1:194
	ds_read2_b64 v[176:179], v2 offset0:224 offset1:226
	ds_read2_b64 v[212:215], v17 offset0:164 offset1:166
	ds_read2_b64 v[216:219], v211 offset0:196 offset1:198
	ds_read2_b64 v[220:223], v2 offset0:228 offset1:230
	s_waitcnt lgkmcnt(7)
	v_mfma_f32_32x32x16_bf16 v[66:81], v[98:101], v[82:85], v[66:81]
	s_waitcnt lgkmcnt(5)
	v_mfma_f32_32x32x16_bf16 v[50:65], v[106:109], v[82:85], v[50:65]
	s_waitcnt lgkmcnt(4)
	v_mfma_f32_32x32x16_bf16 v[34:49], v[110:113], v[82:85], v[34:49]
	s_waitcnt lgkmcnt(3)
	v_mfma_f32_32x32x16_bf16 v[18:33], v[176:179], v[82:85], v[18:33]
	ds_read2_b64 v[82:85], v16 offset0:136 offset1:138
	ds_read2_b64 v[98:101], v17 offset0:168 offset1:170
	ds_read2_b64 v[106:109], v211 offset0:200 offset1:202
	ds_read2_b64 v[110:113], v2 offset0:232 offset1:234
	v_mfma_f32_32x32x16_bf16 v[66:81], v[102:105], v[86:89], v[66:81]
	s_waitcnt lgkmcnt(6)
	v_mfma_f32_32x32x16_bf16 v[50:65], v[212:215], v[86:89], v[50:65]
	s_waitcnt lgkmcnt(5)
	v_mfma_f32_32x32x16_bf16 v[34:49], v[216:219], v[86:89], v[34:49]
	s_waitcnt lgkmcnt(4)
	v_mfma_f32_32x32x16_bf16 v[18:33], v[220:223], v[86:89], v[18:33]
	ds_read2_b64 v[86:89], v16 offset0:140 offset1:142
	ds_read2_b64 v[102:105], v17 offset0:172 offset1:174
	ds_read2_b64 v[176:179], v211 offset0:204 offset1:206
	ds_read2_b64 v[212:215], v2 offset0:236 offset1:238
	s_waitcnt lgkmcnt(7)
	v_mfma_f32_32x32x16_bf16 v[66:81], v[82:85], v[90:93], v[66:81]
	s_waitcnt lgkmcnt(6)
	v_mfma_f32_32x32x16_bf16 v[50:65], v[98:101], v[90:93], v[50:65]
	s_waitcnt lgkmcnt(5)
	v_mfma_f32_32x32x16_bf16 v[34:49], v[106:109], v[90:93], v[34:49]
	s_waitcnt lgkmcnt(4)
	v_mfma_f32_32x32x16_bf16 v[18:33], v[110:113], v[90:93], v[18:33]
	s_waitcnt lgkmcnt(3)
	v_mfma_f32_32x32x16_bf16 v[66:81], v[86:89], v[94:97], v[66:81]
	v_add_f32_e32 v172, v172, v175
	s_waitcnt lgkmcnt(2)
	v_mfma_f32_32x32x16_bf16 v[50:65], v[102:105], v[94:97], v[50:65]
	s_waitcnt lgkmcnt(1)
	v_mfma_f32_32x32x16_bf16 v[34:49], v[176:179], v[94:97], v[34:49]
	s_waitcnt lgkmcnt(0)
	v_mfma_f32_32x32x16_bf16 v[18:33], v[212:215], v[94:97], v[18:33]

.LBB0_932:
	s_nop 10
	v_max_f32_e32 v2, v98, v82
	v_max3_f32 v2, v2, v99, v83
	v_max3_f32 v2, v2, v100, v84
	v_max3_f32 v2, v2, v101, v85
	v_max3_f32 v2, v2, v102, v86
	v_max3_f32 v2, v2, v103, v87
	v_max3_f32 v2, v2, v104, v88
	v_max3_f32 v2, v2, v105, v89
	v_max3_f32 v2, v2, v106, v90
	v_max3_f32 v2, v2, v107, v91
	v_max3_f32 v2, v2, v108, v92
	v_max3_f32 v2, v2, v109, v93
	v_max3_f32 v2, v2, v110, v94
	v_max3_f32 v2, v2, v111, v95
	v_max3_f32 v2, v2, v112, v96
	v_max3_f32 v2, v2, v113, v97
	v_mov_b32_e32 v4, v2
	s_nop 1
	v_permlane32_swap_b32_e32 v2, v4
	v_max_f32_e32 v2, v2, v4
	s_or_b64 s[10:11], s[16:17], s[10:11]
	v_cndmask_b32_e64 v2, v210, v2, s[10:11]
	v_max_f32_e32 v2, v174, v2
	v_cmp_neq_f32_e32 vcc, v2, v174
	s_cbranch_vccz .LBB0_935
	v_sub_f32_e32 v4, v174, v2
	v_mul_f32_e32 v4, 0x3e0293ee, v4
	v_exp_f32_e32 v4, v4
	s_nop 0
	v_pk_mul_f32 v[80:81], v[80:81], v[4:5] op_sel_hi:[1,0]
	v_pk_mul_f32 v[78:79], v[78:79], v[4:5] op_sel_hi:[1,0]
	v_pk_mul_f32 v[76:77], v[76:77], v[4:5] op_sel_hi:[1,0]
	v_pk_mul_f32 v[74:75], v[74:75], v[4:5] op_sel_hi:[1,0]
	v_pk_mul_f32 v[72:73], v[72:73], v[4:5] op_sel_hi:[1,0]
	v_pk_mul_f32 v[70:71], v[70:71], v[4:5] op_sel_hi:[1,0]
	v_pk_mul_f32 v[68:69], v[68:69], v[4:5] op_sel_hi:[1,0]
	v_pk_mul_f32 v[66:67], v[66:67], v[4:5] op_sel_hi:[1,0]
	v_pk_mul_f32 v[64:65], v[64:65], v[4:5] op_sel_hi:[1,0]
	v_pk_mul_f32 v[62:63], v[62:63], v[4:5] op_sel_hi:[1,0]
	v_pk_mul_f32 v[60:61], v[60:61], v[4:5] op_sel_hi:[1,0]
	v_pk_mul_f32 v[58:59], v[58:59], v[4:5] op_sel_hi:[1,0]
	v_pk_mul_f32 v[56:57], v[56:57], v[4:5] op_sel_hi:[1,0]
	v_pk_mul_f32 v[54:55], v[54:55], v[4:5] op_sel_hi:[1,0]
	v_pk_mul_f32 v[52:53], v[52:53], v[4:5] op_sel_hi:[1,0]
	v_pk_mul_f32 v[50:51], v[50:51], v[4:5] op_sel_hi:[1,0]
	v_pk_mul_f32 v[48:49], v[48:49], v[4:5] op_sel_hi:[1,0]
	v_pk_mul_f32 v[46:47], v[46:47], v[4:5] op_sel_hi:[1,0]
	v_pk_mul_f32 v[44:45], v[44:45], v[4:5] op_sel_hi:[1,0]
	v_pk_mul_f32 v[42:43], v[42:43], v[4:5] op_sel_hi:[1,0]
	v_pk_mul_f32 v[40:41], v[40:41], v[4:5] op_sel_hi:[1,0]
	v_pk_mul_f32 v[38:39], v[38:39], v[4:5] op_sel_hi:[1,0]
	v_pk_mul_f32 v[36:37], v[36:37], v[4:5] op_sel_hi:[1,0]
	v_pk_mul_f32 v[34:35], v[34:35], v[4:5] op_sel_hi:[1,0]
	v_pk_mul_f32 v[32:33], v[32:33], v[4:5] op_sel_hi:[1,0]
	v_pk_mul_f32 v[30:31], v[30:31], v[4:5] op_sel_hi:[1,0]
	v_pk_mul_f32 v[28:29], v[28:29], v[4:5] op_sel_hi:[1,0]
	v_pk_mul_f32 v[26:27], v[26:27], v[4:5] op_sel_hi:[1,0]
	v_pk_mul_f32 v[24:25], v[24:25], v[4:5] op_sel_hi:[1,0]
	v_pk_mul_f32 v[22:23], v[22:23], v[4:5] op_sel_hi:[1,0]
	v_pk_mul_f32 v[20:21], v[20:21], v[4:5] op_sel_hi:[1,0]
	v_pk_mul_f32 v[18:19], v[18:19], v[4:5] op_sel_hi:[1,0]
	v_mul_f32_e32 v172, v172, v4
	s_branch .LBB0_936

.LBB0_936:
	v_mul_f32_e32 v114, 0xbe0293ee, v2
	v_cndmask_b32_e64 v114, v210, v114, s[10:11]
	v_fmamk_f32 v2, v98, 0x3e0293ee, v114
	v_exp_f32_e32 v115, v2
	v_fmamk_f32 v2, v82, 0x3e0293ee, v114
	v_exp_f32_e32 v116, v2
	v_fmamk_f32 v2, v99, 0x3e0293ee, v114
	v_fmamk_f32 v4, v83, 0x3e0293ee, v114
	v_exp_f32_e32 v2, v2
	v_exp_f32_e32 v12, v4
	v_add_f32_e32 v13, v116, v115
	v_fmamk_f32 v6, v85, 0x3e0293ee, v114
	v_exp_f32_e32 v14, v6
	v_pk_add_f32 v[4:5], v[12:13], v[2:3]
	v_fmamk_f32 v8, v87, 0x3e0293ee, v114
	v_pk_add_f32 v[4:5], v[4:5], v[4:5] op_sel_hi:[0,1]
	v_fmamk_f32 v4, v100, 0x3e0293ee, v114
	v_exp_f32_e32 v13, v4
	v_fmamk_f32 v4, v84, 0x3e0293ee, v114
	v_exp_f32_e32 v100, v4
	v_fmamk_f32 v4, v101, 0x3e0293ee, v114
	v_exp_f32_e32 v4, v4
	v_exp_f32_e32 v16, v8
	v_add_f32_e32 v15, v100, v13
	v_fmamk_f32 v10, v89, 0x3e0293ee, v114
	v_pk_add_f32 v[6:7], v[14:15], v[4:5]
	v_fmamk_f32 v5, v102, 0x3e0293ee, v114
	v_pk_add_f32 v[6:7], v[6:7], v[6:7] op_sel_hi:[0,1]
	v_fmamk_f32 v6, v86, 0x3e0293ee, v114
	v_exp_f32_e32 v5, v5
	v_exp_f32_e32 v15, v6
	v_fmamk_f32 v6, v103, 0x3e0293ee, v114
	v_exp_f32_e32 v6, v6
	v_exp_f32_e32 v82, v10
	v_add_f32_e32 v17, v15, v5
	v_fmamk_f32 v84, v91, 0x3e0293ee, v114
	v_pk_add_f32 v[8:9], v[16:17], v[6:7]
	v_fmamk_f32 v7, v104, 0x3e0293ee, v114
	v_pk_add_f32 v[8:9], v[8:9], v[8:9] op_sel_hi:[0,1]
	v_fmamk_f32 v8, v88, 0x3e0293ee, v114
	v_exp_f32_e32 v7, v7
	v_exp_f32_e32 v17, v8
	v_fmamk_f32 v8, v105, 0x3e0293ee, v114
	v_exp_f32_e32 v8, v8
	v_exp_f32_e32 v84, v84
	v_add_f32_e32 v83, v17, v7
	v_fmamk_f32 v88, v93, 0x3e0293ee, v114
	v_pk_add_f32 v[10:11], v[82:83], v[8:9]
	v_fmamk_f32 v9, v106, 0x3e0293ee, v114
	v_pk_add_f32 v[10:11], v[10:11], v[10:11] op_sel_hi:[0,1]
	v_fmamk_f32 v10, v90, 0x3e0293ee, v114
	v_exp_f32_e32 v9, v9
	v_exp_f32_e32 v83, v10
	v_fmamk_f32 v10, v107, 0x3e0293ee, v114
	v_exp_f32_e32 v10, v10
	v_exp_f32_e32 v88, v88
	v_add_f32_e32 v85, v83, v9
	v_cvt_pk_bf16_f32 v2, v115, v2
	v_pk_add_f32 v[86:87], v[84:85], v[10:11]
	v_fmamk_f32 v11, v108, 0x3e0293ee, v114
	v_pk_add_f32 v[86:87], v[86:87], v[86:87] op_sel_hi:[0,1]
	v_fmamk_f32 v85, v92, 0x3e0293ee, v114
	v_exp_f32_e32 v11, v11
	v_exp_f32_e32 v85, v85
	v_fmamk_f32 v86, v109, 0x3e0293ee, v114
	v_exp_f32_e32 v86, v86
	v_fmamk_f32 v92, v95, 0x3e0293ee, v114
	v_add_f32_e32 v89, v85, v11
	v_exp_f32_e32 v92, v92
	v_pk_add_f32 v[90:91], v[88:89], v[86:87]
	v_fmamk_f32 v87, v110, 0x3e0293ee, v114
	v_pk_add_f32 v[90:91], v[90:91], v[90:91] op_sel_hi:[0,1]
	v_fmamk_f32 v89, v94, 0x3e0293ee, v114
	v_exp_f32_e32 v87, v87
	v_exp_f32_e32 v89, v89
	v_fmamk_f32 v90, v111, 0x3e0293ee, v114
	v_exp_f32_e32 v90, v90
	v_cvt_pk_bf16_f32 v13, v13, v4
	v_add_f32_e32 v93, v89, v87
	v_mov_b32_e32 v4, v2
	v_pk_add_f32 v[94:95], v[92:93], v[90:91]
	v_fmamk_f32 v91, v112, 0x3e0293ee, v114
	v_pk_add_f32 v[94:95], v[94:95], v[94:95] op_sel_hi:[0,1]
	v_fmamk_f32 v93, v96, 0x3e0293ee, v114
	v_exp_f32_e32 v91, v91
	v_exp_f32_e32 v93, v93
	v_fmamk_f32 v94, v113, 0x3e0293ee, v114
	v_fmac_f32_e32 v114, 0x3e0293ee, v97
	v_exp_f32_e32 v94, v94
	v_exp_f32_e32 v98, v114
	v_add_f32_e32 v99, v93, v91
	v_cvt_pk_bf16_f32 v2, v9, v10
	v_cvt_pk_bf16_f32 v7, v7, v8
	v_pk_add_f32 v[96:97], v[98:99], v[94:95]
	v_mov_b32_e32 v8, v2
	v_pk_add_f32 v[96:97], v[96:97], v[96:97] op_sel:[0,1] op_sel_hi:[1,0]
	v_cvt_pk_bf16_f32 v12, v116, v12
	v_mov_b32_e32 v95, v96
	v_cvt_pk_bf16_f32 v2, v83, v84
	v_permlane32_swap_b32_e32 v96, v95
	v_cvt_pk_bf16_f32 v6, v5, v6
	v_mov_b32_e32 v5, v13
	v_cvt_pk_bf16_f32 v13, v100, v14
	v_cvt_pk_bf16_f32 v14, v15, v16
	v_cvt_pk_bf16_f32 v15, v17, v82
	v_cvt_pk_bf16_f32 v83, v85, v88
	v_cvt_pk_bf16_f32 v84, v89, v92
	v_mov_b32_e32 v82, v2
	v_add3_u32 v2, s14, v163, v206
	v_add_f32_e32 v95, v96, v95
	v_add_u32_e32 v16, 0x4000, v2
	v_add_u32_e32 v17, 0x5000, v2
	v_add_u32_e32 v119, 0x6000, v2
	v_add_u32_e32 v2, 0x7000, v2
	v_cndmask_b32_e64 v118, 0, v95, s[10:11]
	v_cvt_pk_bf16_f32 v9, v11, v86
	v_cvt_pk_bf16_f32 v10, v87, v90
	v_cvt_pk_bf16_f32 v11, v91, v94
	v_cvt_pk_bf16_f32 v85, v93, v98
	ds_read2_b64 v[86:89], v16 offset0:128 offset1:130
	ds_read2_b64 v[90:93], v16 offset0:132 offset1:134
	ds_read2_b64 v[94:97], v17 offset0:160 offset1:162
	ds_read2_b64 v[98:101], v119 offset0:192 offset1:194
	ds_read2_b64 v[102:105], v2 offset0:224 offset1:226
	ds_read2_b64 v[106:109], v17 offset0:164 offset1:166
	ds_read2_b64 v[110:113], v119 offset0:196 offset1:198
	ds_read2_b64 v[114:117], v2 offset0:228 offset1:230
	s_waitcnt lgkmcnt(7)
	v_mfma_f32_32x32x16_bf16 v[66:81], v[86:89], v[4:7], v[66:81]
	s_waitcnt lgkmcnt(5)
	v_mfma_f32_32x32x16_bf16 v[50:65], v[94:97], v[4:7], v[50:65]
	s_waitcnt lgkmcnt(4)
	v_mfma_f32_32x32x16_bf16 v[34:49], v[98:101], v[4:7], v[34:49]
	s_waitcnt lgkmcnt(3)
	v_mfma_f32_32x32x16_bf16 v[18:33], v[102:105], v[4:7], v[18:33]
	ds_read2_b64 v[4:7], v16 offset0:136 offset1:138
	ds_read2_b64 v[86:89], v17 offset0:168 offset1:170
	ds_read2_b64 v[94:97], v119 offset0:200 offset1:202
	ds_read2_b64 v[98:101], v2 offset0:232 offset1:234
	v_mfma_f32_32x32x16_bf16 v[66:81], v[90:93], v[8:11], v[66:81]
	s_waitcnt lgkmcnt(6)
	v_mfma_f32_32x32x16_bf16 v[50:65], v[106:109], v[8:11], v[50:65]
	s_waitcnt lgkmcnt(5)
	v_mfma_f32_32x32x16_bf16 v[34:49], v[110:113], v[8:11], v[34:49]
	s_waitcnt lgkmcnt(4)
	v_mfma_f32_32x32x16_bf16 v[18:33], v[114:117], v[8:11], v[18:33]
	ds_read2_b64 v[8:11], v16 offset0:140 offset1:142
	ds_read2_b64 v[90:93], v17 offset0:172 offset1:174
	ds_read2_b64 v[102:105], v119 offset0:204 offset1:206
	ds_read2_b64 v[106:109], v2 offset0:236 offset1:238
	s_waitcnt lgkmcnt(7)
	v_mfma_f32_32x32x16_bf16 v[66:81], v[4:7], v[12:15], v[66:81]
	s_waitcnt lgkmcnt(6)
	v_mfma_f32_32x32x16_bf16 v[50:65], v[86:89], v[12:15], v[50:65]
	s_waitcnt lgkmcnt(5)
	v_mfma_f32_32x32x16_bf16 v[34:49], v[94:97], v[12:15], v[34:49]
	s_waitcnt lgkmcnt(4)
	v_mfma_f32_32x32x16_bf16 v[18:33], v[98:101], v[12:15], v[18:33]
	s_waitcnt lgkmcnt(3)
	v_mfma_f32_32x32x16_bf16 v[66:81], v[8:11], v[82:85], v[66:81]
	v_add_f32_e32 v172, v172, v118
	s_waitcnt lgkmcnt(2)
	v_mfma_f32_32x32x16_bf16 v[50:65], v[90:93], v[82:85], v[50:65]
	s_waitcnt lgkmcnt(1)
	v_mfma_f32_32x32x16_bf16 v[34:49], v[102:105], v[82:85], v[34:49]
	s_waitcnt lgkmcnt(0)
	v_mfma_f32_32x32x16_bf16 v[18:33], v[106:109], v[82:85], v[18:33]
